# batched (software-pipelined) wo and ple epilogue loops, rewritten inproj/q-up copy-out loops (16 LDS reads + 16 stores back to back)
# speedup vs baseline: 1.0459x; 1.0208x over previous
; DI int tid_() { int t = threadIdx.x; asm volatile("" : "+v"(t)); return t; }
; template <int MODE>
; DI void phase_inproj(const Params& P, char* shm) {
;     ...
; #pragma unroll 4
;     for (int i = 0; i < 16; ++i) {
;       const int chunk = tid_() + i * 512, row = chunk >> 5, c8 = (chunk & 31) * 8;
;       const i32x4 v = *(const i32x4*)(shm + row * 528 + c8 * 2);
;       const int gcol = bcol + c8;
;       u16* d = nullptr;
;       if (MODE == 0) {
;         if (gcol < 448) d = (u16*)(P.ws + OFF_PROJC) + (size_t)(brow + row) * 448 + gcol;
;         else if (gcol >= 512) d = (u16*)(P.ws + OFF_ACTC) + (size_t)(brow + row) * 512 + (gcol - 512);
;       } else if (MODE == 1) {
;         if (gcol < 1024) d = (u16*)(P.ws + OFF_PROJD) + (size_t)(brow + row) * 1024 + gcol;
;         else if (gcol < 1536) {
;           const int c2 = gcol - c8 - 1024 + row;
;           const int b = brow >> 13, s0 = brow & 8191;
;           d = (u16*)(P.ws + OFF_VTD) + ((size_t)((b * 4 + (c2 >> 7)) * 128 + (c2 & 127))) * SEQ + s0 + c8;
;         } else d = (u16*)(P.ws + OFF_ACTD) + (size_t)(brow + row) * 512 + (gcol - 1536);
;       } else if (MODE == 2) {
;         if (gcol < 1024) d = (u16*)(P.ws + OFF_PROJA) + (size_t)(brow + row) * 1024 + gcol;
;         else d = (u16*)(P.ws + OFF_ACTA) + (size_t)(brow + row) * 512 + (gcol - 1024);
;       } else {
;         if (gcol < 512) d = (u16*)(P.ws + OFF_PROJB) + (size_t)(brow + row) * 512 + gcol;
;         else d = (u16*)(P.ws + OFF_ACTB) + (size_t)(brow + row) * 512 + (gcol - 512);
;       }
;       if (d) *(i32x4*)d = v;
;     }
.LBB0_214:
	v_mov_b32_e32 v80, 0
	v_mov_b32_e32 v81, 0
	v_mov_b32_e32 v82, 0
	v_mov_b32_e32 v83, 0
	s_waitcnt lgkmcnt(0)
	v_mov_b32_e32 v0, v135
	s_nop 0
	v_add_u32_e32 v1, s11, v0
	v_ashrrev_i32_e32 v4, 5, v1
	v_lshlrev_b32_e32 v0, 3, v0
	v_and_b32_e32 v5, 0xf8, v0
	v_mul_lo_u32 v0, v4, s68
	v_lshl_add_u32 v0, v5, 1, v0
	v_or_b32_e32 v6, s12, v5
	v_add_u32_e32 v8, s10, v4
	v_cmp_lt_i32_e64 s[4:5], s2, v6
	v_ashrrev_i32_e32 v9, 31, v8
	s_and_saveexec_b64 s[0:1], s[4:5]
	s_xor_b64 s[0:1], exec, s[0:1]
	s_cbranch_execz .LBB0_229
	v_lshlrev_b64 v[4:5], 10, v[8:9]
	v_lshl_add_u64 v[4:5], s[6:7], 0, v[4:5]
	v_mov_b32_e32 v7, v133
	v_lshl_add_u64 v[4:5], v[6:7], 1, v[4:5]
	v_lshl_add_u64 v[4:5], v[4:5], 0, s[18:19]
	v_cndmask_b32_e32 v5, 0, v5, vcc
	v_cndmask_b32_e32 v4, 0, v4, vcc
	s_andn2_saveexec_b64 s[0:1], s[0:1]
	s_cbranch_execnz .LBB0_230

; DI int tid_() { int t = threadIdx.x; asm volatile("" : "+v"(t)); return t; }
; template <int MODE>
; DI void phase_inproj(const Params& P, char* shm) {
;     ...
; #pragma unroll 4
;     for (int i = 0; i < 16; ++i) {
;       const int chunk = tid_() + i * 512, row = chunk >> 5, c8 = (chunk & 31) * 8;
;       const i32x4 v = *(const i32x4*)(shm + row * 528 + c8 * 2);
;       const int gcol = bcol + c8;
;       u16* d = nullptr;
;       if (MODE == 0) {
;         if (gcol < 448) d = (u16*)(P.ws + OFF_PROJC) + (size_t)(brow + row) * 448 + gcol;
;         else if (gcol >= 512) d = (u16*)(P.ws + OFF_ACTC) + (size_t)(brow + row) * 512 + (gcol - 512);
;       } else if (MODE == 1) {
;         if (gcol < 1024) d = (u16*)(P.ws + OFF_PROJD) + (size_t)(brow + row) * 1024 + gcol;
;         else if (gcol < 1536) {
;           const int c2 = gcol - c8 - 1024 + row;
;           const int b = brow >> 13, s0 = brow & 8191;
;           d = (u16*)(P.ws + OFF_VTD) + ((size_t)((b * 4 + (c2 >> 7)) * 128 + (c2 & 127))) * SEQ + s0 + c8;
;         } else d = (u16*)(P.ws + OFF_ACTD) + (size_t)(brow + row) * 512 + (gcol - 1536);
;       } else if (MODE == 2) {
;         if (gcol < 1024) d = (u16*)(P.ws + OFF_PROJA) + (size_t)(brow + row) * 1024 + gcol;
;         else d = (u16*)(P.ws + OFF_ACTA) + (size_t)(brow + row) * 512 + (gcol - 1024);
;       } else {
;         if (gcol < 512) d = (u16*)(P.ws + OFF_PROJB) + (size_t)(brow + row) * 512 + gcol;
;         else d = (u16*)(P.ws + OFF_ACTB) + (size_t)(brow + row) * 512 + (gcol - 512);
;       }
;       if (d) *(i32x4*)d = v;
;     }
.LBB0_217:
	s_waitcnt lgkmcnt(0)
	v_mov_b32_e32 v80, v4
	v_mov_b32_e32 v81, v5
.LBB0_218:
	s_or_b64 exec, exec, s[0:1]
	s_waitcnt lgkmcnt(0)
	v_mov_b32_e32 v0, v135
	s_nop 0
	v_add_u32_e32 v1, s11, v0
	v_add_u32_e32 v1, 0x200, v1
	v_ashrrev_i32_e32 v4, 5, v1
	v_lshlrev_b32_e32 v0, 3, v0
	v_and_b32_e32 v5, 0xf8, v0
	v_mul_lo_u32 v0, v4, s68
	v_lshl_add_u32 v0, v5, 1, v0
	v_or_b32_e32 v132, s12, v5
	v_add_u32_e32 v6, s10, v4
	v_cmp_lt_i32_e64 s[4:5], s2, v132
	v_ashrrev_i32_e32 v7, 31, v6
	s_and_saveexec_b64 s[0:1], s[4:5]
	s_xor_b64 s[0:1], exec, s[0:1]
	s_cbranch_execz .LBB0_231
	v_lshlrev_b64 v[4:5], 10, v[6:7]
	v_lshl_add_u64 v[4:5], s[6:7], 0, v[4:5]
	v_lshl_add_u64 v[4:5], v[132:133], 1, v[4:5]
	v_lshl_add_u64 v[4:5], v[4:5], 0, s[18:19]
	v_cndmask_b32_e32 v5, 0, v5, vcc
	v_cndmask_b32_e32 v4, 0, v4, vcc
	s_andn2_saveexec_b64 s[0:1], s[0:1]
	s_cbranch_execnz .LBB0_232

; DI int tid_() { int t = threadIdx.x; asm volatile("" : "+v"(t)); return t; }
; template <int MODE>
; DI void phase_inproj(const Params& P, char* shm) {
;     ...
; #pragma unroll 4
;     for (int i = 0; i < 16; ++i) {
;       const int chunk = tid_() + i * 512, row = chunk >> 5, c8 = (chunk & 31) * 8;
;       const i32x4 v = *(const i32x4*)(shm + row * 528 + c8 * 2);
;       const int gcol = bcol + c8;
;       u16* d = nullptr;
;       if (MODE == 0) {
;         if (gcol < 448) d = (u16*)(P.ws + OFF_PROJC) + (size_t)(brow + row) * 448 + gcol;
;         else if (gcol >= 512) d = (u16*)(P.ws + OFF_ACTC) + (size_t)(brow + row) * 512 + (gcol - 512);
;       } else if (MODE == 1) {
;         if (gcol < 1024) d = (u16*)(P.ws + OFF_PROJD) + (size_t)(brow + row) * 1024 + gcol;
;         else if (gcol < 1536) {
;           const int c2 = gcol - c8 - 1024 + row;
;           const int b = brow >> 13, s0 = brow & 8191;
;           d = (u16*)(P.ws + OFF_VTD) + ((size_t)((b * 4 + (c2 >> 7)) * 128 + (c2 & 127))) * SEQ + s0 + c8;
;         } else d = (u16*)(P.ws + OFF_ACTD) + (size_t)(brow + row) * 512 + (gcol - 1536);
;       } else if (MODE == 2) {
;         if (gcol < 1024) d = (u16*)(P.ws + OFF_PROJA) + (size_t)(brow + row) * 1024 + gcol;
;         else d = (u16*)(P.ws + OFF_ACTA) + (size_t)(brow + row) * 512 + (gcol - 1024);
;       } else {
;         if (gcol < 512) d = (u16*)(P.ws + OFF_PROJB) + (size_t)(brow + row) * 512 + gcol;
;         else d = (u16*)(P.ws + OFF_ACTB) + (size_t)(brow + row) * 512 + (gcol - 512);
;       }
;       if (d) *(i32x4*)d = v;
;     }
.LBB0_221:
	s_waitcnt lgkmcnt(0)
	v_mov_b32_e32 v82, v4
	v_mov_b32_e32 v83, v5
.LBB0_222:
	s_or_b64 exec, exec, s[0:1]
	s_branch .Lco_fast_214
.Lco_fast_214:
	v_sub_u32_e32 v84, v82, v80
	v_mov_b32_e32 v85, 0
	v_lshrrev_b32_e32 v86, 5, v135
	v_mul_lo_u32 v86, v86, s68
	v_and_b32_e32 v87, 31, v135
	v_lshl_add_u32 v86, v87, 4, v86
	v_add_u32_e32 v87, 0x10800, v86
	ds_read_b128 v[16:19], v86
	ds_read_b128 v[20:23], v86 offset:8448
	ds_read_b128 v[24:27], v86 offset:16896
	ds_read_b128 v[28:31], v86 offset:25344
	ds_read_b128 v[32:35], v86 offset:33792
	ds_read_b128 v[36:39], v86 offset:42240
	ds_read_b128 v[40:43], v86 offset:50688
	ds_read_b128 v[44:47], v86 offset:59136
	ds_read_b128 v[48:51], v87
	ds_read_b128 v[52:55], v87 offset:8448
	ds_read_b128 v[56:59], v87 offset:16896
	ds_read_b128 v[60:63], v87 offset:25344
	ds_read_b128 v[64:67], v87 offset:33792
	ds_read_b128 v[68:71], v87 offset:42240
	ds_read_b128 v[72:75], v87 offset:50688
	ds_read_b128 v[76:79], v87 offset:59136
	v_cmp_ne_u64_e64 s[100:101], 0, v[80:81]
	s_and_saveexec_b64 s[98:99], s[100:101]
	s_cbranch_execz .Lco_done_214
	s_waitcnt lgkmcnt(15)
	global_store_dwordx4 v[80:81], v[16:19], off
	s_nop 0
	v_lshl_add_u64 v[80:81], v[80:81], 0, v[84:85]
	s_waitcnt lgkmcnt(14)
	global_store_dwordx4 v[80:81], v[20:23], off
	s_nop 0
	v_lshl_add_u64 v[80:81], v[80:81], 0, v[84:85]
	s_waitcnt lgkmcnt(13)
	global_store_dwordx4 v[80:81], v[24:27], off
	s_nop 0
	v_lshl_add_u64 v[80:81], v[80:81], 0, v[84:85]
	s_waitcnt lgkmcnt(12)
	global_store_dwordx4 v[80:81], v[28:31], off
	s_nop 0
	v_lshl_add_u64 v[80:81], v[80:81], 0, v[84:85]
	s_waitcnt lgkmcnt(11)
	global_store_dwordx4 v[80:81], v[32:35], off
	s_nop 0
	v_lshl_add_u64 v[80:81], v[80:81], 0, v[84:85]
	s_waitcnt lgkmcnt(10)
	global_store_dwordx4 v[80:81], v[36:39], off
	s_nop 0
	v_lshl_add_u64 v[80:81], v[80:81], 0, v[84:85]
	s_waitcnt lgkmcnt(9)
	global_store_dwordx4 v[80:81], v[40:43], off
	s_nop 0
	v_lshl_add_u64 v[80:81], v[80:81], 0, v[84:85]
	s_waitcnt lgkmcnt(8)
	global_store_dwordx4 v[80:81], v[44:47], off
	s_nop 0
	v_lshl_add_u64 v[80:81], v[80:81], 0, v[84:85]
	s_waitcnt lgkmcnt(7)
	global_store_dwordx4 v[80:81], v[48:51], off
	s_nop 0
	v_lshl_add_u64 v[80:81], v[80:81], 0, v[84:85]
	s_waitcnt lgkmcnt(6)
	global_store_dwordx4 v[80:81], v[52:55], off
	s_nop 0
	v_lshl_add_u64 v[80:81], v[80:81], 0, v[84:85]
	s_waitcnt lgkmcnt(5)
	global_store_dwordx4 v[80:81], v[56:59], off
	s_nop 0
	v_lshl_add_u64 v[80:81], v[80:81], 0, v[84:85]
	s_waitcnt lgkmcnt(4)
	global_store_dwordx4 v[80:81], v[60:63], off
	s_nop 0
	v_lshl_add_u64 v[80:81], v[80:81], 0, v[84:85]
	s_waitcnt lgkmcnt(3)
	global_store_dwordx4 v[80:81], v[64:67], off
	s_nop 0
	v_lshl_add_u64 v[80:81], v[80:81], 0, v[84:85]
	s_waitcnt lgkmcnt(2)
	global_store_dwordx4 v[80:81], v[68:71], off
	s_nop 0
	v_lshl_add_u64 v[80:81], v[80:81], 0, v[84:85]
	s_waitcnt lgkmcnt(1)
	global_store_dwordx4 v[80:81], v[72:75], off
	s_nop 0
	v_lshl_add_u64 v[80:81], v[80:81], 0, v[84:85]
	s_waitcnt lgkmcnt(0)
	global_store_dwordx4 v[80:81], v[76:79], off
.Lco_done_214:
	s_or_b64 exec, exec, s[98:99]
	s_waitcnt lgkmcnt(0)
	s_branch .LBB0_143
	s_waitcnt lgkmcnt(0)
	v_mov_b32_e32 v0, v135
	s_nop 0
	v_add_u32_e32 v1, s11, v0
	v_add_u32_e32 v1, 0x400, v1
	v_ashrrev_i32_e32 v4, 5, v1
	v_lshlrev_b32_e32 v0, 3, v0
	v_and_b32_e32 v5, 0xf8, v0
	v_mul_lo_u32 v0, v4, s68
	v_lshl_add_u32 v0, v5, 1, v0
	ds_read_b128 v[0:3], v0
	v_or_b32_e32 v132, s12, v5
	v_add_u32_e32 v6, s10, v4
	v_cmp_lt_i32_e64 s[4:5], s2, v132
	v_ashrrev_i32_e32 v7, 31, v6
	s_and_saveexec_b64 s[0:1], s[4:5]
	s_xor_b64 s[0:1], exec, s[0:1]
	s_cbranch_execz .LBB0_233
	v_lshlrev_b64 v[4:5], 10, v[6:7]
	v_lshl_add_u64 v[4:5], s[6:7], 0, v[4:5]
	v_lshl_add_u64 v[4:5], v[132:133], 1, v[4:5]
	v_lshl_add_u64 v[4:5], v[4:5], 0, s[18:19]
	v_cndmask_b32_e32 v5, 0, v5, vcc
	v_cndmask_b32_e32 v4, 0, v4, vcc
	s_andn2_saveexec_b64 s[0:1], s[0:1]
	s_cbranch_execnz .LBB0_234

; DI int tid_() { int t = threadIdx.x; asm volatile("" : "+v"(t)); return t; }
; template <int MODE>
; DI void phase_inproj(const Params& P, char* shm) {
;     ...
; #pragma unroll 4
;     for (int i = 0; i < 16; ++i) {
;       const int chunk = tid_() + i * 512, row = chunk >> 5, c8 = (chunk & 31) * 8;
;       const i32x4 v = *(const i32x4*)(shm + row * 528 + c8 * 2);
;       const int gcol = bcol + c8;
;       u16* d = nullptr;
;       if (MODE == 0) {
;         if (gcol < 448) d = (u16*)(P.ws + OFF_PROJC) + (size_t)(brow + row) * 448 + gcol;
;         else if (gcol >= 512) d = (u16*)(P.ws + OFF_ACTC) + (size_t)(brow + row) * 512 + (gcol - 512);
;       } else if (MODE == 1) {
;         if (gcol < 1024) d = (u16*)(P.ws + OFF_PROJD) + (size_t)(brow + row) * 1024 + gcol;
;         else if (gcol < 1536) {
;           const int c2 = gcol - c8 - 1024 + row;
;           const int b = brow >> 13, s0 = brow & 8191;
;           d = (u16*)(P.ws + OFF_VTD) + ((size_t)((b * 4 + (c2 >> 7)) * 128 + (c2 & 127))) * SEQ + s0 + c8;
;         } else d = (u16*)(P.ws + OFF_ACTD) + (size_t)(brow + row) * 512 + (gcol - 1536);
;       } else if (MODE == 2) {
;         if (gcol < 1024) d = (u16*)(P.ws + OFF_PROJA) + (size_t)(brow + row) * 1024 + gcol;
;         else d = (u16*)(P.ws + OFF_ACTA) + (size_t)(brow + row) * 512 + (gcol - 1024);
;       } else {
;         if (gcol < 512) d = (u16*)(P.ws + OFF_PROJB) + (size_t)(brow + row) * 512 + gcol;
;         else d = (u16*)(P.ws + OFF_ACTB) + (size_t)(brow + row) * 512 + (gcol - 512);
;       }
;       if (d) *(i32x4*)d = v;
;     }
.LBB0_319:
	v_mov_b32_e32 v80, 0
	v_mov_b32_e32 v81, 0
	v_mov_b32_e32 v82, 0
	v_mov_b32_e32 v83, 0
	s_nop 0
	v_mov_b32_e32 v0, v135
	s_nop 0
	v_add_u32_e32 v1, s15, v0
	v_ashrrev_i32_e32 v8, 5, v1
	v_lshlrev_b32_e32 v0, 3, v0
	v_and_b32_e32 v9, 0xf8, v0
	v_mul_lo_u32 v0, v8, s68
	v_lshl_add_u32 v0, v9, 1, v0
	v_or_b32_e32 v6, s14, v9
	v_cmp_lt_i32_e32 vcc, s91, v6
	s_and_saveexec_b64 s[6:7], vcc
	s_xor_b64 s[6:7], exec, s[6:7]
	s_cbranch_execz .LBB0_325
	s_mov_b64 s[16:17], -1
	s_and_b64 vcc, exec, s[0:1]
	s_cbranch_vccz .LBB0_322
	v_add_u32_e32 v4, s12, v8
	v_ashrrev_i32_e32 v5, 31, v4
	v_lshlrev_b64 v[4:5], 10, v[4:5]
	v_lshl_add_u64 v[4:5], s[8:9], 0, v[4:5]
	v_mov_b32_e32 v7, v133
	v_lshl_add_u64 v[4:5], v[6:7], 1, v[4:5]
	v_lshl_add_u64 v[4:5], v[4:5], 0, s[44:45]
	s_mov_b64 s[16:17], 0

; DI int tid_() { int t = threadIdx.x; asm volatile("" : "+v"(t)); return t; }
; template <int MODE>
; DI void phase_inproj(const Params& P, char* shm) {
;     ...
; #pragma unroll 4
;     for (int i = 0; i < 16; ++i) {
;       const int chunk = tid_() + i * 512, row = chunk >> 5, c8 = (chunk & 31) * 8;
;       const i32x4 v = *(const i32x4*)(shm + row * 528 + c8 * 2);
;       const int gcol = bcol + c8;
;       u16* d = nullptr;
;       if (MODE == 0) {
;         if (gcol < 448) d = (u16*)(P.ws + OFF_PROJC) + (size_t)(brow + row) * 448 + gcol;
;         else if (gcol >= 512) d = (u16*)(P.ws + OFF_ACTC) + (size_t)(brow + row) * 512 + (gcol - 512);
;       } else if (MODE == 1) {
;         if (gcol < 1024) d = (u16*)(P.ws + OFF_PROJD) + (size_t)(brow + row) * 1024 + gcol;
;         else if (gcol < 1536) {
;           const int c2 = gcol - c8 - 1024 + row;
;           const int b = brow >> 13, s0 = brow & 8191;
;           d = (u16*)(P.ws + OFF_VTD) + ((size_t)((b * 4 + (c2 >> 7)) * 128 + (c2 & 127))) * SEQ + s0 + c8;
;         } else d = (u16*)(P.ws + OFF_ACTD) + (size_t)(brow + row) * 512 + (gcol - 1536);
;       } else if (MODE == 2) {
;         if (gcol < 1024) d = (u16*)(P.ws + OFF_PROJA) + (size_t)(brow + row) * 1024 + gcol;
;         else d = (u16*)(P.ws + OFF_ACTA) + (size_t)(brow + row) * 512 + (gcol - 1024);
;       } else {
;         if (gcol < 512) d = (u16*)(P.ws + OFF_PROJB) + (size_t)(brow + row) * 512 + gcol;
;         else d = (u16*)(P.ws + OFF_ACTB) + (size_t)(brow + row) * 512 + (gcol - 512);
;       }
;       if (d) *(i32x4*)d = v;
;     }
.LBB0_324:
.LBB0_325:
	s_andn2_saveexec_b64 s[6:7], s[6:7]
	v_add_u32_e32 v4, s12, v8
	v_ashrrev_i32_e32 v5, 31, v4
	v_lshlrev_b64 v[4:5], 11, v[4:5]
	v_lshl_add_u64 v[4:5], s[10:11], 0, v[4:5]
	v_ashrrev_i32_e32 v7, 31, v6
	v_lshl_add_u64 v[4:5], v[6:7], 1, v[4:5]
	s_or_b64 exec, exec, s[6:7]
	s_waitcnt lgkmcnt(0)
	v_mov_b32_e32 v80, v4
	v_mov_b32_e32 v81, v5
	v_cndmask_b32_e64 v4, 0, 1, s[0:1]
	v_cmp_ne_u32_e64 s[6:7], 1, v4
	v_mov_b32_e32 v0, v135
	s_nop 0
	v_add_u32_e32 v1, s15, v0
	v_add_u32_e32 v1, 0x200, v1
	v_ashrrev_i32_e32 v6, 5, v1
	v_lshlrev_b32_e32 v0, 3, v0
	v_and_b32_e32 v7, 0xf8, v0
	v_mul_lo_u32 v0, v6, s68
	v_lshl_add_u32 v0, v7, 1, v0
	v_or_b32_e32 v132, s14, v7
	v_cmp_lt_i32_e32 vcc, s91, v132
	s_and_saveexec_b64 s[16:17], vcc
	s_xor_b64 s[16:17], exec, s[16:17]
	s_cbranch_execz .LBB0_333
	s_and_b64 vcc, exec, s[6:7]
	s_mov_b64 s[18:19], -1
	s_cbranch_vccnz .LBB0_330
	v_add_u32_e32 v4, s12, v6
	v_ashrrev_i32_e32 v5, 31, v4
	v_lshlrev_b64 v[4:5], 10, v[4:5]
	v_lshl_add_u64 v[4:5], s[8:9], 0, v[4:5]
	v_lshl_add_u64 v[4:5], v[132:133], 1, v[4:5]
	v_lshl_add_u64 v[4:5], v[4:5], 0, s[44:45]
	s_mov_b64 s[18:19], 0

; DI int tid_() { int t = threadIdx.x; asm volatile("" : "+v"(t)); return t; }
; template <int MODE>
; DI void phase_inproj(const Params& P, char* shm) {
;     ...
; #pragma unroll 4
;     for (int i = 0; i < 16; ++i) {
;       const int chunk = tid_() + i * 512, row = chunk >> 5, c8 = (chunk & 31) * 8;
;       const i32x4 v = *(const i32x4*)(shm + row * 528 + c8 * 2);
;       const int gcol = bcol + c8;
;       u16* d = nullptr;
;       if (MODE == 0) {
;         if (gcol < 448) d = (u16*)(P.ws + OFF_PROJC) + (size_t)(brow + row) * 448 + gcol;
;         else if (gcol >= 512) d = (u16*)(P.ws + OFF_ACTC) + (size_t)(brow + row) * 512 + (gcol - 512);
;       } else if (MODE == 1) {
;         if (gcol < 1024) d = (u16*)(P.ws + OFF_PROJD) + (size_t)(brow + row) * 1024 + gcol;
;         else if (gcol < 1536) {
;           const int c2 = gcol - c8 - 1024 + row;
;           const int b = brow >> 13, s0 = brow & 8191;
;           d = (u16*)(P.ws + OFF_VTD) + ((size_t)((b * 4 + (c2 >> 7)) * 128 + (c2 & 127))) * SEQ + s0 + c8;
;         } else d = (u16*)(P.ws + OFF_ACTD) + (size_t)(brow + row) * 512 + (gcol - 1536);
;       } else if (MODE == 2) {
;         if (gcol < 1024) d = (u16*)(P.ws + OFF_PROJA) + (size_t)(brow + row) * 1024 + gcol;
;         else d = (u16*)(P.ws + OFF_ACTA) + (size_t)(brow + row) * 512 + (gcol - 1024);
;       } else {
;         if (gcol < 512) d = (u16*)(P.ws + OFF_PROJB) + (size_t)(brow + row) * 512 + gcol;
;         else d = (u16*)(P.ws + OFF_ACTB) + (size_t)(brow + row) * 512 + (gcol - 512);
;       }
;       if (d) *(i32x4*)d = v;
;     }
.LBB0_332:
.LBB0_333:
	s_andn2_saveexec_b64 s[16:17], s[16:17]
	v_add_u32_e32 v4, s12, v6
	v_ashrrev_i32_e32 v5, 31, v4
	v_lshlrev_b64 v[4:5], 11, v[4:5]
	v_lshl_add_u64 v[4:5], s[10:11], 0, v[4:5]
	v_ashrrev_i32_e32 v7, 31, v132
	v_mov_b32_e32 v6, v132
	v_lshl_add_u64 v[4:5], v[6:7], 1, v[4:5]
	s_or_b64 exec, exec, s[16:17]
	s_waitcnt lgkmcnt(0)
	v_mov_b32_e32 v82, v4
	v_mov_b32_e32 v83, v5
	s_branch .Lco_fast_319

; DI int tid_() { int t = threadIdx.x; asm volatile("" : "+v"(t)); return t; }
; template <int MODE>
; DI void phase_inproj(const Params& P, char* shm) {
;     ...
; #pragma unroll 4
;     for (int i = 0; i < 16; ++i) {
;       const int chunk = tid_() + i * 512, row = chunk >> 5, c8 = (chunk & 31) * 8;
;       const i32x4 v = *(const i32x4*)(shm + row * 528 + c8 * 2);
;       const int gcol = bcol + c8;
;       u16* d = nullptr;
;       if (MODE == 0) {
;         if (gcol < 448) d = (u16*)(P.ws + OFF_PROJC) + (size_t)(brow + row) * 448 + gcol;
;         else if (gcol >= 512) d = (u16*)(P.ws + OFF_ACTC) + (size_t)(brow + row) * 512 + (gcol - 512);
;       } else if (MODE == 1) {
;         if (gcol < 1024) d = (u16*)(P.ws + OFF_PROJD) + (size_t)(brow + row) * 1024 + gcol;
;         else if (gcol < 1536) {
;           const int c2 = gcol - c8 - 1024 + row;
;           const int b = brow >> 13, s0 = brow & 8191;
;           d = (u16*)(P.ws + OFF_VTD) + ((size_t)((b * 4 + (c2 >> 7)) * 128 + (c2 & 127))) * SEQ + s0 + c8;
;         } else d = (u16*)(P.ws + OFF_ACTD) + (size_t)(brow + row) * 512 + (gcol - 1536);
;       } else if (MODE == 2) {
;         if (gcol < 1024) d = (u16*)(P.ws + OFF_PROJA) + (size_t)(brow + row) * 1024 + gcol;
;         else d = (u16*)(P.ws + OFF_ACTA) + (size_t)(brow + row) * 512 + (gcol - 1024);
;       } else {
;         if (gcol < 512) d = (u16*)(P.ws + OFF_PROJB) + (size_t)(brow + row) * 512 + gcol;
;         else d = (u16*)(P.ws + OFF_ACTB) + (size_t)(brow + row) * 512 + (gcol - 512);
;       }
;       if (d) *(i32x4*)d = v;
;     }
.Lco_done_319:
	s_or_b64 exec, exec, s[98:99]
	s_waitcnt lgkmcnt(0)
	s_branch .LBB0_240
	s_nop 1
	v_mov_b32_e32 v0, v135
	s_nop 0
	v_add_u32_e32 v1, s15, v0
	v_add_u32_e32 v1, 0x400, v1
	v_ashrrev_i32_e32 v6, 5, v1
	v_lshlrev_b32_e32 v0, 3, v0
	v_and_b32_e32 v7, 0xf8, v0
	v_mul_lo_u32 v0, v6, s68
	v_lshl_add_u32 v0, v7, 1, v0
	ds_read_b128 v[0:3], v0
	v_or_b32_e32 v132, s14, v7
	v_cmp_lt_i32_e32 vcc, s91, v132
	s_and_saveexec_b64 s[16:17], vcc
	s_xor_b64 s[16:17], exec, s[16:17]
	s_cbranch_execz .LBB0_341
	s_and_b64 vcc, exec, s[6:7]
	s_mov_b64 s[18:19], -1
	s_cbranch_vccnz .LBB0_338
	v_add_u32_e32 v4, s12, v6
	v_ashrrev_i32_e32 v5, 31, v4
	v_lshlrev_b64 v[4:5], 10, v[4:5]
	v_lshl_add_u64 v[4:5], s[8:9], 0, v[4:5]
	v_lshl_add_u64 v[4:5], v[132:133], 1, v[4:5]
	v_lshl_add_u64 v[4:5], v[4:5], 0, s[44:45]
	s_mov_b64 s[18:19], 0

; DI int tid_() { int t = threadIdx.x; asm volatile("" : "+v"(t)); return t; }
; DI void phase_mla_up(const Params& P, int l, char* shm) {
;     ...
; #pragma unroll 4
;     for (int i = 0; i < 16; ++i) {
;       const int chunk = tid_() + i * 512, row = chunk >> 5, c8 = (chunk & 31) * 8;
;       const i32x4 v = *(const i32x4*)(shm + row * 528 + c8 * 2);
;       *(i32x4*)((u16*)(P.ws + OFF_QRAW) + (size_t)(brow + row) * 768 + bcol + c8) = v;
;     }
;     __syncthreads();
.LBB0_556:
	v_mov_b32_e32 v80, 0
	v_mov_b32_e32 v81, 0
	v_mov_b32_e32 v82, 0
	v_mov_b32_e32 v83, 0
	v_mov_b32_e32 v0, v135
	s_nop 0
	v_add_u32_e32 v1, s4, v0
	v_lshlrev_b32_e32 v0, 4, v0
	v_ashrrev_i32_e32 v6, 5, v1
	v_and_b32_e32 v132, 0x1f0, v0
	v_mad_u64_u32 v[0:1], s[6:7], v6, s68, v[132:133]
	v_add_u32_e32 v6, s17, v6
	v_mov_b64_e32 v[0:1], s[0:1]
	v_mad_i64_i32 v[6:7], s[6:7], v6, s3, v[0:1]
	v_lshl_add_u64 v[6:7], v[6:7], 0, v[132:133]
	s_waitcnt lgkmcnt(0)
	v_mov_b32_e32 v80, v6
	v_mov_b32_e32 v81, v7
	s_nop 1
	v_mov_b32_e32 v2, v135
	s_nop 0
	v_add_u32_e32 v3, s4, v2
	v_add_u32_e32 v3, 0x200, v3
	v_lshlrev_b32_e32 v2, 4, v2
	v_ashrrev_i32_e32 v6, 5, v3
	v_and_b32_e32 v132, 0x1f0, v2
	v_mad_u64_u32 v[2:3], s[6:7], v6, s68, v[132:133]
	v_add_u32_e32 v6, s17, v6
	v_mad_i64_i32 v[6:7], s[6:7], v6, s3, v[0:1]
	v_lshl_add_u64 v[6:7], v[6:7], 0, v[132:133]
	s_waitcnt lgkmcnt(0)
	v_mov_b32_e32 v82, v6
	v_mov_b32_e32 v83, v7
	s_branch .Lco_fast_556

; DI int tid_() { int t = threadIdx.x; asm volatile("" : "+v"(t)); return t; }
; DI void phase_mla_up(const Params& P, int l, char* shm) {
;     ...
; #pragma unroll 4
;     for (int i = 0; i < 16; ++i) {
;       const int chunk = tid_() + i * 512, row = chunk >> 5, c8 = (chunk & 31) * 8;
;       const i32x4 v = *(const i32x4*)(shm + row * 528 + c8 * 2);
;       *(i32x4*)((u16*)(P.ws + OFF_QRAW) + (size_t)(brow + row) * 768 + bcol + c8) = v;
;     }
;     __syncthreads();
.Lco_done_556:
	s_or_b64 exec, exec, s[98:99]
	s_waitcnt lgkmcnt(0)
	s_branch .Lco_exit_556
	s_nop 1
	v_mov_b32_e32 v2, v135
	s_nop 0
	v_add_u32_e32 v3, s4, v2
	v_add_u32_e32 v3, 0x400, v3
	v_lshlrev_b32_e32 v2, 4, v2
	v_ashrrev_i32_e32 v6, 5, v3
	v_and_b32_e32 v132, 0x1f0, v2
	v_mad_u64_u32 v[2:3], s[6:7], v6, s68, v[132:133]
	ds_read_b128 v[2:5], v2
	v_add_u32_e32 v6, s17, v6
	v_mad_i64_i32 v[6:7], s[6:7], v6, s3, v[0:1]
	v_lshl_add_u64 v[6:7], v[6:7], 0, v[132:133]
	s_waitcnt lgkmcnt(0)
	global_store_dwordx4 v[6:7], v[2:5], off
	s_nop 1
	v_mov_b32_e32 v2, v135
	s_nop 0
	v_add_u32_e32 v3, s4, v2
	v_add_u32_e32 v3, 0x600, v3
	v_lshlrev_b32_e32 v2, 4, v2
	v_ashrrev_i32_e32 v6, 5, v3
	v_and_b32_e32 v132, 0x1f0, v2
	v_mad_u64_u32 v[2:3], s[6:7], v6, s68, v[132:133]
	ds_read_b128 v[2:5], v2
	v_add_u32_e32 v6, s17, v6
	v_mad_i64_i32 v[0:1], s[6:7], v6, s3, v[0:1]
	s_addk_i32 s4, 0x800
	v_lshl_add_u64 v[0:1], v[0:1], 0, v[132:133]
	s_cmpk_eq_i32 s4, 0x2000
	s_waitcnt lgkmcnt(0)
	global_store_dwordx4 v[0:1], v[2:5], off
	s_cbranch_scc0 .LBB0_556
.Lco_exit_556:
	s_add_i32 s16, s16, s72
	s_cmpk_gt_i32 s16, 0x17f
	s_waitcnt lgkmcnt(0)
	s_barrier
	s_cbranch_scc0 .LBB0_547

; DI int tid_() { int t = threadIdx.x; asm volatile("" : "+v"(t)); return t; }
; template <int MODE>
; DI void phase_inproj(const Params& P, char* shm) {
;     ...
; #pragma unroll 4
;     for (int i = 0; i < 16; ++i) {
;       const int chunk = tid_() + i * 512, row = chunk >> 5, c8 = (chunk & 31) * 8;
;       const i32x4 v = *(const i32x4*)(shm + row * 528 + c8 * 2);
;       const int gcol = bcol + c8;
;       u16* d = nullptr;
;       if (MODE == 0) {
;         if (gcol < 448) d = (u16*)(P.ws + OFF_PROJC) + (size_t)(brow + row) * 448 + gcol;
;         else if (gcol >= 512) d = (u16*)(P.ws + OFF_ACTC) + (size_t)(brow + row) * 512 + (gcol - 512);
;       } else if (MODE == 1) {
;         if (gcol < 1024) d = (u16*)(P.ws + OFF_PROJD) + (size_t)(brow + row) * 1024 + gcol;
;         else if (gcol < 1536) {
;           const int c2 = gcol - c8 - 1024 + row;
;           const int b = brow >> 13, s0 = brow & 8191;
;           d = (u16*)(P.ws + OFF_VTD) + ((size_t)((b * 4 + (c2 >> 7)) * 128 + (c2 & 127))) * SEQ + s0 + c8;
;         } else d = (u16*)(P.ws + OFF_ACTD) + (size_t)(brow + row) * 512 + (gcol - 1536);
;       } else if (MODE == 2) {
;         if (gcol < 1024) d = (u16*)(P.ws + OFF_PROJA) + (size_t)(brow + row) * 1024 + gcol;
;         else d = (u16*)(P.ws + OFF_ACTA) + (size_t)(brow + row) * 512 + (gcol - 1024);
;       } else {
;         if (gcol < 512) d = (u16*)(P.ws + OFF_PROJB) + (size_t)(brow + row) * 512 + gcol;
;         else d = (u16*)(P.ws + OFF_ACTB) + (size_t)(brow + row) * 512 + (gcol - 512);
;       }
;       if (d) *(i32x4*)d = v;
;     }
.LBB0_657:
	v_mov_b32_e32 v80, 0
	v_mov_b32_e32 v81, 0
	v_mov_b32_e32 v82, 0
	v_mov_b32_e32 v83, 0
	s_nop 0
	v_mov_b32_e32 v0, v135
	s_nop 0
	v_add_u32_e32 v1, s4, v0
	v_ashrrev_i32_e32 v5, 5, v1
	v_lshlrev_b32_e32 v0, 3, v0
	v_and_b32_e32 v4, 0xf8, v0
	v_mul_lo_u32 v0, v5, s68
	v_lshl_add_u32 v0, v4, 1, v0
	v_or_b32_e32 v4, s14, v4
	v_add_u32_e32 v8, s12, v5
	v_cmp_lt_i32_e32 vcc, s91, v4
	v_ashrrev_i32_e32 v9, 31, v8
	s_and_saveexec_b64 s[0:1], vcc
	s_xor_b64 s[0:1], exec, s[0:1]
	v_lshlrev_b64 v[6:7], 10, v[8:9]
	v_lshl_add_u64 v[6:7], s[8:9], 0, v[6:7]
	v_mov_b32_e32 v5, v133
	v_lshl_add_u64 v[4:5], v[4:5], 1, v[6:7]
	v_lshl_add_u64 v[6:7], v[4:5], 0, s[24:25]
	s_andn2_saveexec_b64 s[0:1], s[0:1]
	v_lshlrev_b64 v[6:7], 11, v[8:9]
	v_lshl_add_u64 v[6:7], s[10:11], 0, v[6:7]
	v_ashrrev_i32_e32 v5, 31, v4
	v_lshl_add_u64 v[6:7], v[4:5], 1, v[6:7]
	s_or_b64 exec, exec, s[0:1]
	s_waitcnt lgkmcnt(0)
	v_mov_b32_e32 v80, v6
	v_mov_b32_e32 v81, v7
	s_nop 1
	v_mov_b32_e32 v0, v135
	s_nop 0
	v_add_u32_e32 v1, s4, v0
	v_add_u32_e32 v1, 0x200, v1
	v_ashrrev_i32_e32 v4, 5, v1
	v_lshlrev_b32_e32 v0, 3, v0
	v_and_b32_e32 v5, 0xf8, v0
	v_mul_lo_u32 v0, v4, s68
	v_lshl_add_u32 v0, v5, 1, v0
	v_or_b32_e32 v132, s14, v5
	v_add_u32_e32 v6, s12, v4
	v_cmp_lt_i32_e32 vcc, s91, v132
	v_ashrrev_i32_e32 v7, 31, v6
	s_and_saveexec_b64 s[0:1], vcc
	s_xor_b64 s[0:1], exec, s[0:1]
	v_lshlrev_b64 v[4:5], 10, v[6:7]
	v_lshl_add_u64 v[4:5], s[8:9], 0, v[4:5]
	v_lshl_add_u64 v[4:5], v[132:133], 1, v[4:5]
	v_lshl_add_u64 v[4:5], v[4:5], 0, s[24:25]
	s_andn2_saveexec_b64 s[0:1], s[0:1]
	v_lshlrev_b64 v[4:5], 11, v[6:7]
	v_lshl_add_u64 v[4:5], s[10:11], 0, v[4:5]
	v_ashrrev_i32_e32 v7, 31, v132
	v_mov_b32_e32 v6, v132
	v_lshl_add_u64 v[4:5], v[6:7], 1, v[4:5]
	s_or_b64 exec, exec, s[0:1]
	s_waitcnt lgkmcnt(0)
	v_mov_b32_e32 v82, v4
	v_mov_b32_e32 v83, v5
	s_branch .Lco_fast_657

; DI int tid_() { int t = threadIdx.x; asm volatile("" : "+v"(t)); return t; }
; template <int MODE>
; DI void phase_inproj(const Params& P, char* shm) {
;     ...
; #pragma unroll 4
;     for (int i = 0; i < 16; ++i) {
;       const int chunk = tid_() + i * 512, row = chunk >> 5, c8 = (chunk & 31) * 8;
;       const i32x4 v = *(const i32x4*)(shm + row * 528 + c8 * 2);
;       const int gcol = bcol + c8;
;       u16* d = nullptr;
;       if (MODE == 0) {
;         if (gcol < 448) d = (u16*)(P.ws + OFF_PROJC) + (size_t)(brow + row) * 448 + gcol;
;         else if (gcol >= 512) d = (u16*)(P.ws + OFF_ACTC) + (size_t)(brow + row) * 512 + (gcol - 512);
;       } else if (MODE == 1) {
;         if (gcol < 1024) d = (u16*)(P.ws + OFF_PROJD) + (size_t)(brow + row) * 1024 + gcol;
;         else if (gcol < 1536) {
;           const int c2 = gcol - c8 - 1024 + row;
;           const int b = brow >> 13, s0 = brow & 8191;
;           d = (u16*)(P.ws + OFF_VTD) + ((size_t)((b * 4 + (c2 >> 7)) * 128 + (c2 & 127))) * SEQ + s0 + c8;
;         } else d = (u16*)(P.ws + OFF_ACTD) + (size_t)(brow + row) * 512 + (gcol - 1536);
;       } else if (MODE == 2) {
;         if (gcol < 1024) d = (u16*)(P.ws + OFF_PROJA) + (size_t)(brow + row) * 1024 + gcol;
;         else d = (u16*)(P.ws + OFF_ACTA) + (size_t)(brow + row) * 512 + (gcol - 1024);
;       } else {
;         if (gcol < 512) d = (u16*)(P.ws + OFF_PROJB) + (size_t)(brow + row) * 512 + gcol;
;         else d = (u16*)(P.ws + OFF_ACTB) + (size_t)(brow + row) * 512 + (gcol - 512);
;       }
;       if (d) *(i32x4*)d = v;
;     }
.Lco_done_657:
	s_or_b64 exec, exec, s[98:99]
	s_waitcnt lgkmcnt(0)
	s_branch .LBB0_586
	s_nop 1
	v_mov_b32_e32 v0, v135
	s_nop 0
	v_add_u32_e32 v1, s4, v0
	v_add_u32_e32 v1, 0x400, v1
	v_ashrrev_i32_e32 v4, 5, v1
	v_lshlrev_b32_e32 v0, 3, v0
	v_and_b32_e32 v5, 0xf8, v0
	v_mul_lo_u32 v0, v4, s68
	v_lshl_add_u32 v0, v5, 1, v0
	ds_read_b128 v[0:3], v0
	v_or_b32_e32 v132, s14, v5
	v_add_u32_e32 v6, s12, v4
	v_cmp_lt_i32_e32 vcc, s91, v132
	v_ashrrev_i32_e32 v7, 31, v6
	s_and_saveexec_b64 s[0:1], vcc
	s_xor_b64 s[0:1], exec, s[0:1]
	v_lshlrev_b64 v[4:5], 10, v[6:7]
	v_lshl_add_u64 v[4:5], s[8:9], 0, v[4:5]
	v_lshl_add_u64 v[4:5], v[132:133], 1, v[4:5]
	v_lshl_add_u64 v[4:5], v[4:5], 0, s[24:25]
	s_andn2_saveexec_b64 s[0:1], s[0:1]
	v_lshlrev_b64 v[4:5], 11, v[6:7]
	v_lshl_add_u64 v[4:5], s[10:11], 0, v[4:5]
	v_ashrrev_i32_e32 v7, 31, v132
	v_mov_b32_e32 v6, v132
	v_lshl_add_u64 v[4:5], v[6:7], 1, v[4:5]
	s_or_b64 exec, exec, s[0:1]
	s_waitcnt lgkmcnt(0)
	global_store_dwordx4 v[4:5], v[0:3], off
	s_nop 1
	v_mov_b32_e32 v0, v135
	s_nop 0
	v_add_u32_e32 v1, s4, v0
	v_add_u32_e32 v1, 0x600, v1
	v_ashrrev_i32_e32 v4, 5, v1
	v_lshlrev_b32_e32 v0, 3, v0
	v_and_b32_e32 v5, 0xf8, v0
	v_mul_lo_u32 v0, v4, s68
	v_lshl_add_u32 v0, v5, 1, v0
	ds_read_b128 v[0:3], v0
	v_or_b32_e32 v132, s14, v5
	v_add_u32_e32 v6, s12, v4
	v_cmp_lt_i32_e32 vcc, s91, v132
	v_ashrrev_i32_e32 v7, 31, v6
	s_and_saveexec_b64 s[0:1], vcc
	s_xor_b64 s[0:1], exec, s[0:1]
	v_lshlrev_b64 v[4:5], 10, v[6:7]
	v_lshl_add_u64 v[4:5], s[8:9], 0, v[4:5]
	v_lshl_add_u64 v[4:5], v[132:133], 1, v[4:5]
	v_lshl_add_u64 v[4:5], v[4:5], 0, s[24:25]
	s_andn2_saveexec_b64 s[0:1], s[0:1]
	s_cbranch_execz .LBB0_656
	v_lshlrev_b64 v[4:5], 11, v[6:7]
	v_lshl_add_u64 v[4:5], s[10:11], 0, v[4:5]
	v_ashrrev_i32_e32 v7, 31, v132
	v_mov_b32_e32 v6, v132
	v_lshl_add_u64 v[4:5], v[6:7], 1, v[4:5]
	s_branch .LBB0_656

; DI int tid_() { int t = threadIdx.x; asm volatile("" : "+v"(t)); return t; }
; template <int MODE>
; DI void phase_inproj(const Params& P, char* shm) {
;     ...
; #pragma unroll 4
;     for (int i = 0; i < 16; ++i) {
;       const int chunk = tid_() + i * 512, row = chunk >> 5, c8 = (chunk & 31) * 8;
;       const i32x4 v = *(const i32x4*)(shm + row * 528 + c8 * 2);
;       const int gcol = bcol + c8;
;       u16* d = nullptr;
;       if (MODE == 0) {
;         if (gcol < 448) d = (u16*)(P.ws + OFF_PROJC) + (size_t)(brow + row) * 448 + gcol;
;         else if (gcol >= 512) d = (u16*)(P.ws + OFF_ACTC) + (size_t)(brow + row) * 512 + (gcol - 512);
;       } else if (MODE == 1) {
;         if (gcol < 1024) d = (u16*)(P.ws + OFF_PROJD) + (size_t)(brow + row) * 1024 + gcol;
;         else if (gcol < 1536) {
;           const int c2 = gcol - c8 - 1024 + row;
;           const int b = brow >> 13, s0 = brow & 8191;
;           d = (u16*)(P.ws + OFF_VTD) + ((size_t)((b * 4 + (c2 >> 7)) * 128 + (c2 & 127))) * SEQ + s0 + c8;
;         } else d = (u16*)(P.ws + OFF_ACTD) + (size_t)(brow + row) * 512 + (gcol - 1536);
;       } else if (MODE == 2) {
;         if (gcol < 1024) d = (u16*)(P.ws + OFF_PROJA) + (size_t)(brow + row) * 1024 + gcol;
;         else d = (u16*)(P.ws + OFF_ACTA) + (size_t)(brow + row) * 512 + (gcol - 1024);
;       } else {
;         if (gcol < 512) d = (u16*)(P.ws + OFF_PROJB) + (size_t)(brow + row) * 512 + gcol;
;         else d = (u16*)(P.ws + OFF_ACTB) + (size_t)(brow + row) * 512 + (gcol - 512);
;       }
;       if (d) *(i32x4*)d = v;
;     }
.LBB0_746:
	v_mov_b32_e32 v80, 0
	v_mov_b32_e32 v81, 0
	v_mov_b32_e32 v82, 0
	v_mov_b32_e32 v83, 0
	s_nop 0
	v_mov_b32_e32 v0, v135
	s_nop 0
	v_add_u32_e32 v1, s4, v0
	v_ashrrev_i32_e32 v5, 5, v1
	v_lshlrev_b32_e32 v0, 3, v0
	v_and_b32_e32 v4, 0xf8, v0
	v_mul_lo_u32 v0, v5, s68
	v_lshl_add_u32 v0, v4, 1, v0
	v_add_u32_e32 v6, s12, v5
	v_or_b32_e32 v4, s14, v4
	v_ashrrev_i32_e32 v7, 31, v6
	v_cmp_lt_i32_e32 vcc, s89, v4
	v_lshlrev_b64 v[8:9], 10, v[6:7]
	s_and_saveexec_b64 s[0:1], vcc
	s_xor_b64 s[0:1], exec, s[0:1]
	v_lshl_add_u64 v[6:7], s[8:9], 0, v[8:9]
	v_mov_b32_e32 v5, v133
	v_lshl_add_u64 v[4:5], v[4:5], 1, v[6:7]
	v_lshl_add_u64 v[6:7], v[4:5], 0, s[94:95]
	s_andn2_saveexec_b64 s[0:1], s[0:1]
	v_lshl_add_u64 v[6:7], s[10:11], 0, v[8:9]
	v_ashrrev_i32_e32 v5, 31, v4
	v_lshl_add_u64 v[6:7], v[4:5], 1, v[6:7]
	s_or_b64 exec, exec, s[0:1]
	s_waitcnt lgkmcnt(0)
	v_mov_b32_e32 v80, v6
	v_mov_b32_e32 v81, v7
	s_nop 1
	v_mov_b32_e32 v0, v135
	s_nop 0
	v_add_u32_e32 v1, s4, v0
	v_add_u32_e32 v1, 0x200, v1
	v_ashrrev_i32_e32 v4, 5, v1
	v_lshlrev_b32_e32 v0, 3, v0
	v_and_b32_e32 v5, 0xf8, v0
	v_mul_lo_u32 v0, v4, s68
	v_lshl_add_u32 v0, v5, 1, v0
	v_add_u32_e32 v4, s12, v4
	v_or_b32_e32 v132, s14, v5
	v_ashrrev_i32_e32 v5, 31, v4
	v_cmp_lt_i32_e32 vcc, s89, v132
	v_lshlrev_b64 v[6:7], 10, v[4:5]
	s_and_saveexec_b64 s[0:1], vcc
	s_xor_b64 s[0:1], exec, s[0:1]
	v_lshl_add_u64 v[4:5], s[8:9], 0, v[6:7]
	v_lshl_add_u64 v[4:5], v[132:133], 1, v[4:5]
	v_lshl_add_u64 v[4:5], v[4:5], 0, s[94:95]
	s_andn2_saveexec_b64 s[0:1], s[0:1]
	v_lshl_add_u64 v[4:5], s[10:11], 0, v[6:7]
	v_ashrrev_i32_e32 v7, 31, v132
	v_mov_b32_e32 v6, v132
	v_lshl_add_u64 v[4:5], v[6:7], 1, v[4:5]
	s_or_b64 exec, exec, s[0:1]
	s_waitcnt lgkmcnt(0)
	v_mov_b32_e32 v82, v4
	v_mov_b32_e32 v83, v5
	s_branch .Lco_fast_746

; DI int tid_() { int t = threadIdx.x; asm volatile("" : "+v"(t)); return t; }
; template <int MODE>
; DI void phase_inproj(const Params& P, char* shm) {
;     ...
; #pragma unroll 4
;     for (int i = 0; i < 16; ++i) {
;       const int chunk = tid_() + i * 512, row = chunk >> 5, c8 = (chunk & 31) * 8;
;       const i32x4 v = *(const i32x4*)(shm + row * 528 + c8 * 2);
;       const int gcol = bcol + c8;
;       u16* d = nullptr;
;       if (MODE == 0) {
;         if (gcol < 448) d = (u16*)(P.ws + OFF_PROJC) + (size_t)(brow + row) * 448 + gcol;
;         else if (gcol >= 512) d = (u16*)(P.ws + OFF_ACTC) + (size_t)(brow + row) * 512 + (gcol - 512);
;       } else if (MODE == 1) {
;         if (gcol < 1024) d = (u16*)(P.ws + OFF_PROJD) + (size_t)(brow + row) * 1024 + gcol;
;         else if (gcol < 1536) {
;           const int c2 = gcol - c8 - 1024 + row;
;           const int b = brow >> 13, s0 = brow & 8191;
;           d = (u16*)(P.ws + OFF_VTD) + ((size_t)((b * 4 + (c2 >> 7)) * 128 + (c2 & 127))) * SEQ + s0 + c8;
;         } else d = (u16*)(P.ws + OFF_ACTD) + (size_t)(brow + row) * 512 + (gcol - 1536);
;       } else if (MODE == 2) {
;         if (gcol < 1024) d = (u16*)(P.ws + OFF_PROJA) + (size_t)(brow + row) * 1024 + gcol;
;         else d = (u16*)(P.ws + OFF_ACTA) + (size_t)(brow + row) * 512 + (gcol - 1024);
;       } else {
;         if (gcol < 512) d = (u16*)(P.ws + OFF_PROJB) + (size_t)(brow + row) * 512 + gcol;
;         else d = (u16*)(P.ws + OFF_ACTB) + (size_t)(brow + row) * 512 + (gcol - 512);
;       }
;       if (d) *(i32x4*)d = v;
;     }
.Lco_done_746:
	s_or_b64 exec, exec, s[98:99]
	s_waitcnt lgkmcnt(0)
	s_branch .LBB0_675
	s_nop 1
	v_mov_b32_e32 v0, v135
	s_nop 0
	v_add_u32_e32 v1, s4, v0
	v_add_u32_e32 v1, 0x400, v1
	v_ashrrev_i32_e32 v4, 5, v1
	v_lshlrev_b32_e32 v0, 3, v0
	v_and_b32_e32 v5, 0xf8, v0
	v_mul_lo_u32 v0, v4, s68
	v_lshl_add_u32 v0, v5, 1, v0
	ds_read_b128 v[0:3], v0
	v_add_u32_e32 v4, s12, v4
	v_or_b32_e32 v132, s14, v5
	v_ashrrev_i32_e32 v5, 31, v4
	v_cmp_lt_i32_e32 vcc, s89, v132
	v_lshlrev_b64 v[6:7], 10, v[4:5]
	s_and_saveexec_b64 s[0:1], vcc
	s_xor_b64 s[0:1], exec, s[0:1]
	v_lshl_add_u64 v[4:5], s[8:9], 0, v[6:7]
	v_lshl_add_u64 v[4:5], v[132:133], 1, v[4:5]
	v_lshl_add_u64 v[4:5], v[4:5], 0, s[94:95]
	s_andn2_saveexec_b64 s[0:1], s[0:1]
	v_lshl_add_u64 v[4:5], s[10:11], 0, v[6:7]
	v_ashrrev_i32_e32 v7, 31, v132
	v_mov_b32_e32 v6, v132
	v_lshl_add_u64 v[4:5], v[6:7], 1, v[4:5]
	s_or_b64 exec, exec, s[0:1]
	s_waitcnt lgkmcnt(0)
	global_store_dwordx4 v[4:5], v[0:3], off
	s_nop 1
	v_mov_b32_e32 v0, v135
	s_nop 0
	v_add_u32_e32 v1, s4, v0
	v_add_u32_e32 v1, 0x600, v1
	v_ashrrev_i32_e32 v4, 5, v1
	v_lshlrev_b32_e32 v0, 3, v0
	v_and_b32_e32 v5, 0xf8, v0
	v_mul_lo_u32 v0, v4, s68
	v_lshl_add_u32 v0, v5, 1, v0
	ds_read_b128 v[0:3], v0
	v_add_u32_e32 v4, s12, v4
	v_or_b32_e32 v132, s14, v5
	v_ashrrev_i32_e32 v5, 31, v4
	v_cmp_lt_i32_e32 vcc, s89, v132
	v_lshlrev_b64 v[6:7], 10, v[4:5]
	s_and_saveexec_b64 s[0:1], vcc
	s_xor_b64 s[0:1], exec, s[0:1]
	v_lshl_add_u64 v[4:5], s[8:9], 0, v[6:7]
	v_lshl_add_u64 v[4:5], v[132:133], 1, v[4:5]
	v_lshl_add_u64 v[4:5], v[4:5], 0, s[94:95]
	s_andn2_saveexec_b64 s[0:1], s[0:1]
	s_cbranch_execz .LBB0_745
	v_lshl_add_u64 v[4:5], s[10:11], 0, v[6:7]
	v_ashrrev_i32_e32 v7, 31, v132
	v_mov_b32_e32 v6, v132
	v_lshl_add_u64 v[4:5], v[6:7], 1, v[4:5]
	s_branch .LBB0_745

; DI int tid_() { int t = threadIdx.x; asm volatile("" : "+v"(t)); return t; }
; DI void phase_wo(const Params& P, const float* xin, char* shm) {
;     ...
; #pragma unroll 4
;       for (int i = 0; i < 16; ++i) {
;         const int chunk = tid_() + i * 512, row = chunk >> 6, c4 = (chunk & 63) * 4;
;         const f32x4 v = *(const f32x4*)(shm + row * 1040 + c4 * 4);
;         const size_t off = (size_t)(brow + ps * 128 + row) * DM + bcol + c4;
;         const f32x4 xv = *(const f32x4*)(xin + off);
;         *(f32x4*)(P.out + off) = xv + v;
;       }
;       __syncthreads();
.LBB0_879:
.Lwo_p0:
	v_lshrrev_b32_e32 v148, 6, v135
	v_lshlrev_b32_e32 v149, 2, v135
	v_and_b32_e32 v149, 0xfc, v149
	v_mul_lo_u32 v150, v148, s93
	v_lshl_add_u32 v150, v149, 2, v150
	v_add_u32_e32 v152, s10, v148
	v_ashrrev_i32_e32 v153, 31, v152
	v_lshlrev_b64 v[152:153], 10, v[152:153]
	v_lshl_add_u64 v[152:153], v[152:153], 0, s[8:9]
	v_or_b32_e32 v152, v152, v149
	v_lshlrev_b64 v[156:157], 2, v[152:153]
	v_lshl_add_u64 v[238:239], s[6:7], 0, v[156:157]
	v_lshl_add_u64 v[240:241], s[4:5], 0, v[156:157]
	s_mov_b32 s100, 0x8000
	s_mov_b32 s101, 0
	v_add_u32_e32 v242, 0x10400, v150
	global_load_dwordx4 v[158:161], v[238:239], off
	v_lshl_add_u64 v[238:239], v[238:239], 0, s[100:101]
	global_load_dwordx4 v[162:165], v[238:239], off
	v_lshl_add_u64 v[238:239], v[238:239], 0, s[100:101]
	global_load_dwordx4 v[166:169], v[238:239], off
	v_lshl_add_u64 v[238:239], v[238:239], 0, s[100:101]
	global_load_dwordx4 v[170:173], v[238:239], off
	v_lshl_add_u64 v[238:239], v[238:239], 0, s[100:101]
	global_load_dwordx4 v[174:177], v[238:239], off
	v_lshl_add_u64 v[238:239], v[238:239], 0, s[100:101]
	global_load_dwordx4 v[178:181], v[238:239], off
	v_lshl_add_u64 v[238:239], v[238:239], 0, s[100:101]
	global_load_dwordx4 v[182:185], v[238:239], off
	v_lshl_add_u64 v[238:239], v[238:239], 0, s[100:101]
	global_load_dwordx4 v[186:189], v[238:239], off
	v_lshl_add_u64 v[238:239], v[238:239], 0, s[100:101]
	ds_read_b128 v[190:193], v150
	ds_read_b128 v[194:197], v150 offset:8320
	ds_read_b128 v[198:201], v150 offset:16640
	ds_read_b128 v[218:221], v150 offset:24960
	ds_read_b128 v[222:225], v150 offset:33280
	ds_read_b128 v[226:229], v150 offset:41600
	ds_read_b128 v[230:233], v150 offset:49920
	ds_read_b128 v[234:237], v150 offset:58240
	s_waitcnt vmcnt(7) lgkmcnt(7)
	v_pk_add_f32 v[192:193], v[192:193], v[160:161]
	v_pk_add_f32 v[190:191], v[190:191], v[158:159]
	global_store_dwordx4 v[240:241], v[190:193], off
	s_nop 1
	v_lshl_add_u64 v[240:241], v[240:241], 0, s[100:101]
	s_waitcnt vmcnt(7) lgkmcnt(6)
	v_pk_add_f32 v[196:197], v[196:197], v[164:165]
	v_pk_add_f32 v[194:195], v[194:195], v[162:163]
	global_store_dwordx4 v[240:241], v[194:197], off
	s_nop 1
	v_lshl_add_u64 v[240:241], v[240:241], 0, s[100:101]
	s_waitcnt vmcnt(7) lgkmcnt(5)
	v_pk_add_f32 v[200:201], v[200:201], v[168:169]
	v_pk_add_f32 v[198:199], v[198:199], v[166:167]
	global_store_dwordx4 v[240:241], v[198:201], off
	s_nop 1
	v_lshl_add_u64 v[240:241], v[240:241], 0, s[100:101]
	s_waitcnt vmcnt(7) lgkmcnt(4)
	v_pk_add_f32 v[220:221], v[220:221], v[172:173]
	v_pk_add_f32 v[218:219], v[218:219], v[170:171]
	global_store_dwordx4 v[240:241], v[218:221], off
	s_nop 1
	v_lshl_add_u64 v[240:241], v[240:241], 0, s[100:101]
	s_waitcnt vmcnt(7) lgkmcnt(3)
	v_pk_add_f32 v[224:225], v[224:225], v[176:177]
	v_pk_add_f32 v[222:223], v[222:223], v[174:175]
	global_store_dwordx4 v[240:241], v[222:225], off
	s_nop 1
	v_lshl_add_u64 v[240:241], v[240:241], 0, s[100:101]
	s_waitcnt vmcnt(7) lgkmcnt(2)
	v_pk_add_f32 v[228:229], v[228:229], v[180:181]
	v_pk_add_f32 v[226:227], v[226:227], v[178:179]
	global_store_dwordx4 v[240:241], v[226:229], off
	s_nop 1
	v_lshl_add_u64 v[240:241], v[240:241], 0, s[100:101]
	s_waitcnt vmcnt(7) lgkmcnt(1)
	v_pk_add_f32 v[232:233], v[232:233], v[184:185]
	v_pk_add_f32 v[230:231], v[230:231], v[182:183]
	global_store_dwordx4 v[240:241], v[230:233], off
	s_nop 1
	v_lshl_add_u64 v[240:241], v[240:241], 0, s[100:101]
	s_waitcnt vmcnt(7) lgkmcnt(0)
	v_pk_add_f32 v[236:237], v[236:237], v[188:189]
	v_pk_add_f32 v[234:235], v[234:235], v[186:187]
	global_store_dwordx4 v[240:241], v[234:237], off
	s_nop 1
	v_lshl_add_u64 v[240:241], v[240:241], 0, s[100:101]
	global_load_dwordx4 v[158:161], v[238:239], off
	v_lshl_add_u64 v[238:239], v[238:239], 0, s[100:101]
	global_load_dwordx4 v[162:165], v[238:239], off
	v_lshl_add_u64 v[238:239], v[238:239], 0, s[100:101]
	global_load_dwordx4 v[166:169], v[238:239], off
	v_lshl_add_u64 v[238:239], v[238:239], 0, s[100:101]
	global_load_dwordx4 v[170:173], v[238:239], off
	v_lshl_add_u64 v[238:239], v[238:239], 0, s[100:101]
	global_load_dwordx4 v[174:177], v[238:239], off
	v_lshl_add_u64 v[238:239], v[238:239], 0, s[100:101]
	global_load_dwordx4 v[178:181], v[238:239], off
	v_lshl_add_u64 v[238:239], v[238:239], 0, s[100:101]
	global_load_dwordx4 v[182:185], v[238:239], off
	v_lshl_add_u64 v[238:239], v[238:239], 0, s[100:101]
	global_load_dwordx4 v[186:189], v[238:239], off
	v_lshl_add_u64 v[238:239], v[238:239], 0, s[100:101]
	ds_read_b128 v[190:193], v242
	ds_read_b128 v[194:197], v242 offset:8320
	ds_read_b128 v[198:201], v242 offset:16640
	ds_read_b128 v[218:221], v242 offset:24960
	ds_read_b128 v[222:225], v242 offset:33280
	ds_read_b128 v[226:229], v242 offset:41600
	ds_read_b128 v[230:233], v242 offset:49920
	ds_read_b128 v[234:237], v242 offset:58240
	s_waitcnt vmcnt(7) lgkmcnt(7)
	v_pk_add_f32 v[192:193], v[192:193], v[160:161]
	v_pk_add_f32 v[190:191], v[190:191], v[158:159]
	global_store_dwordx4 v[240:241], v[190:193], off
	s_nop 1
	v_lshl_add_u64 v[240:241], v[240:241], 0, s[100:101]
	s_waitcnt vmcnt(7) lgkmcnt(6)
	v_pk_add_f32 v[196:197], v[196:197], v[164:165]
	v_pk_add_f32 v[194:195], v[194:195], v[162:163]
	global_store_dwordx4 v[240:241], v[194:197], off
	s_nop 1
	v_lshl_add_u64 v[240:241], v[240:241], 0, s[100:101]
	s_waitcnt vmcnt(7) lgkmcnt(5)
	v_pk_add_f32 v[200:201], v[200:201], v[168:169]
	v_pk_add_f32 v[198:199], v[198:199], v[166:167]
	global_store_dwordx4 v[240:241], v[198:201], off
	s_nop 1
	v_lshl_add_u64 v[240:241], v[240:241], 0, s[100:101]
	s_waitcnt vmcnt(7) lgkmcnt(4)
	v_pk_add_f32 v[220:221], v[220:221], v[172:173]
	v_pk_add_f32 v[218:219], v[218:219], v[170:171]
	global_store_dwordx4 v[240:241], v[218:221], off
	s_nop 1
	v_lshl_add_u64 v[240:241], v[240:241], 0, s[100:101]
	s_waitcnt vmcnt(7) lgkmcnt(3)
	v_pk_add_f32 v[224:225], v[224:225], v[176:177]
	v_pk_add_f32 v[222:223], v[222:223], v[174:175]
	global_store_dwordx4 v[240:241], v[222:225], off
	s_nop 1
	v_lshl_add_u64 v[240:241], v[240:241], 0, s[100:101]
	s_waitcnt vmcnt(7) lgkmcnt(2)
	v_pk_add_f32 v[228:229], v[228:229], v[180:181]
	v_pk_add_f32 v[226:227], v[226:227], v[178:179]
	global_store_dwordx4 v[240:241], v[226:229], off
	s_nop 1
	v_lshl_add_u64 v[240:241], v[240:241], 0, s[100:101]
	s_waitcnt vmcnt(7) lgkmcnt(1)
	v_pk_add_f32 v[232:233], v[232:233], v[184:185]
	v_pk_add_f32 v[230:231], v[230:231], v[182:183]
	global_store_dwordx4 v[240:241], v[230:233], off
	s_nop 1
	v_lshl_add_u64 v[240:241], v[240:241], 0, s[100:101]
	s_waitcnt vmcnt(7) lgkmcnt(0)
	v_pk_add_f32 v[236:237], v[236:237], v[188:189]
	v_pk_add_f32 v[234:235], v[234:235], v[186:187]
	global_store_dwordx4 v[240:241], v[234:237], off
	s_nop 1
	v_lshl_add_u64 v[240:241], v[240:241], 0, s[100:101]
	s_waitcnt lgkmcnt(0)
	s_barrier
; DI void phase_wo(const Params& P, const float* xin, char* shm) {
;     ...
;       if (wr == ps) {
; #pragma unroll
;         for (int m = 0; m < 8; ++m)
; #pragma unroll
;           for (int n = 0; n < 4; ++n) {
;             const int row = m * 16 + fr, col = wc * 64 + n * 16 + fq * 4;
;             *(f32x4*)(shm + row * 1040 + col * 4) = acc[m][n];
;           }
;       }
	s_and_saveexec_b64 s[12:13], s[0:1]
	s_cbranch_execz .LBB0_882
	ds_write_b128 v128, v[124:127]
	ds_write_b128 v128, v[120:123] offset:64
	ds_write_b128 v128, v[116:119] offset:128
	ds_write_b128 v128, v[112:115] offset:192
	ds_write_b128 v128, v[108:111] offset:16640
	ds_write_b128 v128, v[104:107] offset:16704
	ds_write_b128 v128, v[100:103] offset:16768
	ds_write_b128 v128, v[96:99] offset:16832
	ds_write_b128 v128, v[92:95] offset:33280
	ds_write_b128 v128, v[88:91] offset:33344
	ds_write_b128 v128, v[84:87] offset:33408
	ds_write_b128 v128, v[80:83] offset:33472
	ds_write_b128 v128, v[76:79] offset:49920
	ds_write_b128 v128, v[72:75] offset:49984
	ds_write_b128 v128, v[68:71] offset:50048
	ds_write_b128 v128, v[64:67] offset:50112
	ds_write_b128 v129, v[60:63]
	ds_write_b128 v130, v[56:59]
	ds_write_b128 v131, v[52:55]
	ds_write_b128 v132, v[48:51]
	ds_write_b128 v136, v[44:47]
	ds_write_b128 v137, v[40:43]
	ds_write_b128 v138, v[36:39]
	ds_write_b128 v139, v[32:35]
	ds_write_b128 v140, v[28:31]
	ds_write_b128 v141, v[24:27]
	ds_write_b128 v142, v[16:19]
	ds_write_b128 v143, v[12:15]
	ds_write_b128 v144, v[8:11]
	ds_write_b128 v145, v[4:7]
	ds_write_b128 v146, v[0:3]
	ds_write_b128 v147, v[20:23]

; DI int tid_() { int t = threadIdx.x; asm volatile("" : "+v"(t)); return t; }
; DI void phase_wo(const Params& P, const float* xin, char* shm) {
;     ...
; #pragma unroll 4
;       for (int i = 0; i < 16; ++i) {
;         const int chunk = tid_() + i * 512, row = chunk >> 6, c4 = (chunk & 63) * 4;
;         const f32x4 v = *(const f32x4*)(shm + row * 1040 + c4 * 4);
;         const size_t off = (size_t)(brow + ps * 128 + row) * DM + bcol + c4;
;         const f32x4 xv = *(const f32x4*)(xin + off);
;         *(f32x4*)(P.out + off) = xv + v;
;       }
;       __syncthreads();
;     }
;   }
.LBB0_883:
.Lwo_p1:
	v_lshrrev_b32_e32 v148, 6, v135
	v_lshlrev_b32_e32 v149, 2, v135
	v_and_b32_e32 v149, 0xfc, v149
	v_mul_lo_u32 v150, v148, s93
	v_lshl_add_u32 v150, v149, 2, v150
	v_add_u32_e32 v152, s10, v148
	v_ashrrev_i32_e32 v153, 31, v152
	v_lshlrev_b64 v[152:153], 10, v[152:153]
	v_lshl_add_u64 v[152:153], v[152:153], 0, s[8:9]
	v_or_b32_e32 v152, v152, v149
	v_lshlrev_b64 v[156:157], 2, v[152:153]
	v_lshl_add_u64 v[238:239], s[6:7], 0, v[156:157]
	v_lshl_add_u64 v[240:241], s[4:5], 0, v[156:157]
	s_mov_b32 s100, 0x8000
	s_mov_b32 s101, 0
	v_add_u32_e32 v242, 0x10400, v150
	global_load_dwordx4 v[158:161], v[238:239], off
	v_lshl_add_u64 v[238:239], v[238:239], 0, s[100:101]
	global_load_dwordx4 v[162:165], v[238:239], off
	v_lshl_add_u64 v[238:239], v[238:239], 0, s[100:101]
	global_load_dwordx4 v[166:169], v[238:239], off
	v_lshl_add_u64 v[238:239], v[238:239], 0, s[100:101]
	global_load_dwordx4 v[170:173], v[238:239], off
	v_lshl_add_u64 v[238:239], v[238:239], 0, s[100:101]
	global_load_dwordx4 v[174:177], v[238:239], off
	v_lshl_add_u64 v[238:239], v[238:239], 0, s[100:101]
	global_load_dwordx4 v[178:181], v[238:239], off
	v_lshl_add_u64 v[238:239], v[238:239], 0, s[100:101]
	global_load_dwordx4 v[182:185], v[238:239], off
	v_lshl_add_u64 v[238:239], v[238:239], 0, s[100:101]
	global_load_dwordx4 v[186:189], v[238:239], off
	v_lshl_add_u64 v[238:239], v[238:239], 0, s[100:101]
	ds_read_b128 v[190:193], v150
	ds_read_b128 v[194:197], v150 offset:8320
	ds_read_b128 v[198:201], v150 offset:16640
	ds_read_b128 v[218:221], v150 offset:24960
	ds_read_b128 v[222:225], v150 offset:33280
	ds_read_b128 v[226:229], v150 offset:41600
	ds_read_b128 v[230:233], v150 offset:49920
	ds_read_b128 v[234:237], v150 offset:58240
	s_waitcnt vmcnt(7) lgkmcnt(7)
	v_pk_add_f32 v[192:193], v[192:193], v[160:161]
	v_pk_add_f32 v[190:191], v[190:191], v[158:159]
	global_store_dwordx4 v[240:241], v[190:193], off
	s_nop 1
	v_lshl_add_u64 v[240:241], v[240:241], 0, s[100:101]
	s_waitcnt vmcnt(7) lgkmcnt(6)
	v_pk_add_f32 v[196:197], v[196:197], v[164:165]
	v_pk_add_f32 v[194:195], v[194:195], v[162:163]
	global_store_dwordx4 v[240:241], v[194:197], off
	s_nop 1
	v_lshl_add_u64 v[240:241], v[240:241], 0, s[100:101]
	s_waitcnt vmcnt(7) lgkmcnt(5)
	v_pk_add_f32 v[200:201], v[200:201], v[168:169]
	v_pk_add_f32 v[198:199], v[198:199], v[166:167]
	global_store_dwordx4 v[240:241], v[198:201], off
	s_nop 1
	v_lshl_add_u64 v[240:241], v[240:241], 0, s[100:101]
	s_waitcnt vmcnt(7) lgkmcnt(4)
	v_pk_add_f32 v[220:221], v[220:221], v[172:173]
	v_pk_add_f32 v[218:219], v[218:219], v[170:171]
	global_store_dwordx4 v[240:241], v[218:221], off
	s_nop 1
	v_lshl_add_u64 v[240:241], v[240:241], 0, s[100:101]
	s_waitcnt vmcnt(7) lgkmcnt(3)
	v_pk_add_f32 v[224:225], v[224:225], v[176:177]
	v_pk_add_f32 v[222:223], v[222:223], v[174:175]
	global_store_dwordx4 v[240:241], v[222:225], off
	s_nop 1
	v_lshl_add_u64 v[240:241], v[240:241], 0, s[100:101]
	s_waitcnt vmcnt(7) lgkmcnt(2)
	v_pk_add_f32 v[228:229], v[228:229], v[180:181]
	v_pk_add_f32 v[226:227], v[226:227], v[178:179]
	global_store_dwordx4 v[240:241], v[226:229], off
	s_nop 1
	v_lshl_add_u64 v[240:241], v[240:241], 0, s[100:101]
	s_waitcnt vmcnt(7) lgkmcnt(1)
	v_pk_add_f32 v[232:233], v[232:233], v[184:185]
	v_pk_add_f32 v[230:231], v[230:231], v[182:183]
	global_store_dwordx4 v[240:241], v[230:233], off
	s_nop 1
	v_lshl_add_u64 v[240:241], v[240:241], 0, s[100:101]
	s_waitcnt vmcnt(7) lgkmcnt(0)
	v_pk_add_f32 v[236:237], v[236:237], v[188:189]
	v_pk_add_f32 v[234:235], v[234:235], v[186:187]
	global_store_dwordx4 v[240:241], v[234:237], off
	s_nop 1
	v_lshl_add_u64 v[240:241], v[240:241], 0, s[100:101]
	global_load_dwordx4 v[158:161], v[238:239], off
	v_lshl_add_u64 v[238:239], v[238:239], 0, s[100:101]
	global_load_dwordx4 v[162:165], v[238:239], off
	v_lshl_add_u64 v[238:239], v[238:239], 0, s[100:101]
	global_load_dwordx4 v[166:169], v[238:239], off
	v_lshl_add_u64 v[238:239], v[238:239], 0, s[100:101]
	global_load_dwordx4 v[170:173], v[238:239], off
	v_lshl_add_u64 v[238:239], v[238:239], 0, s[100:101]
	global_load_dwordx4 v[174:177], v[238:239], off
	v_lshl_add_u64 v[238:239], v[238:239], 0, s[100:101]
	global_load_dwordx4 v[178:181], v[238:239], off
	v_lshl_add_u64 v[238:239], v[238:239], 0, s[100:101]
	global_load_dwordx4 v[182:185], v[238:239], off
	v_lshl_add_u64 v[238:239], v[238:239], 0, s[100:101]
	global_load_dwordx4 v[186:189], v[238:239], off
	v_lshl_add_u64 v[238:239], v[238:239], 0, s[100:101]
	ds_read_b128 v[190:193], v242
	ds_read_b128 v[194:197], v242 offset:8320
	ds_read_b128 v[198:201], v242 offset:16640
	ds_read_b128 v[218:221], v242 offset:24960
	ds_read_b128 v[222:225], v242 offset:33280
	ds_read_b128 v[226:229], v242 offset:41600
	ds_read_b128 v[230:233], v242 offset:49920
	ds_read_b128 v[234:237], v242 offset:58240
	s_waitcnt vmcnt(7) lgkmcnt(7)
	v_pk_add_f32 v[192:193], v[192:193], v[160:161]
	v_pk_add_f32 v[190:191], v[190:191], v[158:159]
	global_store_dwordx4 v[240:241], v[190:193], off
	s_nop 1
	v_lshl_add_u64 v[240:241], v[240:241], 0, s[100:101]
	s_waitcnt vmcnt(7) lgkmcnt(6)
	v_pk_add_f32 v[196:197], v[196:197], v[164:165]
	v_pk_add_f32 v[194:195], v[194:195], v[162:163]
	global_store_dwordx4 v[240:241], v[194:197], off
	s_nop 1
	v_lshl_add_u64 v[240:241], v[240:241], 0, s[100:101]
	s_waitcnt vmcnt(7) lgkmcnt(5)
	v_pk_add_f32 v[200:201], v[200:201], v[168:169]
	v_pk_add_f32 v[198:199], v[198:199], v[166:167]
	global_store_dwordx4 v[240:241], v[198:201], off
	s_nop 1
	v_lshl_add_u64 v[240:241], v[240:241], 0, s[100:101]
	s_waitcnt vmcnt(7) lgkmcnt(4)
	v_pk_add_f32 v[220:221], v[220:221], v[172:173]
	v_pk_add_f32 v[218:219], v[218:219], v[170:171]
	global_store_dwordx4 v[240:241], v[218:221], off
	s_nop 1
	v_lshl_add_u64 v[240:241], v[240:241], 0, s[100:101]
	s_waitcnt vmcnt(7) lgkmcnt(3)
	v_pk_add_f32 v[224:225], v[224:225], v[176:177]
	v_pk_add_f32 v[222:223], v[222:223], v[174:175]
	global_store_dwordx4 v[240:241], v[222:225], off
	s_nop 1
	v_lshl_add_u64 v[240:241], v[240:241], 0, s[100:101]
	s_waitcnt vmcnt(7) lgkmcnt(2)
	v_pk_add_f32 v[228:229], v[228:229], v[180:181]
	v_pk_add_f32 v[226:227], v[226:227], v[178:179]
	global_store_dwordx4 v[240:241], v[226:229], off
	s_nop 1
	v_lshl_add_u64 v[240:241], v[240:241], 0, s[100:101]
	s_waitcnt vmcnt(7) lgkmcnt(1)
	v_pk_add_f32 v[232:233], v[232:233], v[184:185]
	v_pk_add_f32 v[230:231], v[230:231], v[182:183]
	global_store_dwordx4 v[240:241], v[230:233], off
	s_nop 1
	v_lshl_add_u64 v[240:241], v[240:241], 0, s[100:101]
	s_waitcnt vmcnt(7) lgkmcnt(0)
	v_pk_add_f32 v[236:237], v[236:237], v[188:189]
	v_pk_add_f32 v[234:235], v[234:235], v[186:187]
	global_store_dwordx4 v[240:241], v[234:237], off
	s_nop 1
	v_lshl_add_u64 v[240:241], v[240:241], 0, s[100:101]
	s_add_i32 s20, s20, s72
	s_cmpk_gt_i32 s20, 0x1ff
	s_waitcnt lgkmcnt(0)
	s_barrier
	s_cbranch_scc0 .LBB0_872

; DI int tid_() { int t = threadIdx.x; asm volatile("" : "+v"(t)); return t; }
; DI void phase_ple(const Params& P, char* shm) {
;     ...
; #pragma unroll 4
;     for (int i = 0; i < 16; ++i) {
;       const int chunk = tid_() + i * 512, row = chunk >> 5, c4 = (chunk & 31) * 4;
;       const f32x4 v = *(const f32x4*)(shm + row * 528 + c4 * 4);
;       float* d = P.out + (size_t)(brow + row) * DM + bcol + c4;
;       *(f32x4*)d = *(const f32x4*)d + v;
;     }
;     __syncthreads();
;   }
.LBB0_935:
	v_lshrrev_b32_e32 v0, 5, v135
	v_lshlrev_b32_e32 v1, 4, v135
	v_and_b32_e32 v132, 0x1f0, v1
	v_mul_lo_u32 v6, v0, s68
	v_add_u32_e32 v6, v6, v132
	v_add_u32_e32 v7, 0x10800, v6
	v_add_u32_e32 v4, s4, v0
	v_ashrrev_i32_e32 v5, 31, v4
	v_lshlrev_b64 v[4:5], 12, v[4:5]
	v_lshl_add_u64 v[4:5], s[6:7], 0, v[4:5]
	v_lshl_add_u64 v[4:5], v[4:5], 0, v[132:133]
	v_mov_b32_e32 v2, v4
	v_mov_b32_e32 v3, v5
	s_mov_b32 s100, 0x10000
	s_mov_b32 s101, 0
	global_load_dwordx4 v[16:19], v[2:3], off
	v_lshl_add_u64 v[2:3], v[2:3], 0, s[100:101]
	global_load_dwordx4 v[20:23], v[2:3], off
	v_lshl_add_u64 v[2:3], v[2:3], 0, s[100:101]
	global_load_dwordx4 v[24:27], v[2:3], off
	v_lshl_add_u64 v[2:3], v[2:3], 0, s[100:101]
	global_load_dwordx4 v[28:31], v[2:3], off
	v_lshl_add_u64 v[2:3], v[2:3], 0, s[100:101]
	global_load_dwordx4 v[32:35], v[2:3], off
	v_lshl_add_u64 v[2:3], v[2:3], 0, s[100:101]
	global_load_dwordx4 v[36:39], v[2:3], off
	v_lshl_add_u64 v[2:3], v[2:3], 0, s[100:101]
	global_load_dwordx4 v[40:43], v[2:3], off
	v_lshl_add_u64 v[2:3], v[2:3], 0, s[100:101]
	global_load_dwordx4 v[44:47], v[2:3], off
	v_lshl_add_u64 v[2:3], v[2:3], 0, s[100:101]
	global_load_dwordx4 v[48:51], v[2:3], off
	v_lshl_add_u64 v[2:3], v[2:3], 0, s[100:101]
	global_load_dwordx4 v[52:55], v[2:3], off
	v_lshl_add_u64 v[2:3], v[2:3], 0, s[100:101]
	global_load_dwordx4 v[56:59], v[2:3], off
	v_lshl_add_u64 v[2:3], v[2:3], 0, s[100:101]
	global_load_dwordx4 v[60:63], v[2:3], off
	v_lshl_add_u64 v[2:3], v[2:3], 0, s[100:101]
	global_load_dwordx4 v[64:67], v[2:3], off
	v_lshl_add_u64 v[2:3], v[2:3], 0, s[100:101]
	global_load_dwordx4 v[68:71], v[2:3], off
	v_lshl_add_u64 v[2:3], v[2:3], 0, s[100:101]
	global_load_dwordx4 v[72:75], v[2:3], off
	v_lshl_add_u64 v[2:3], v[2:3], 0, s[100:101]
	global_load_dwordx4 v[76:79], v[2:3], off
	ds_read_b128 v[80:83], v6
	ds_read_b128 v[84:87], v6 offset:8448
	ds_read_b128 v[88:91], v6 offset:16896
	ds_read_b128 v[92:95], v6 offset:25344
	ds_read_b128 v[96:99], v6 offset:33792
	ds_read_b128 v[100:103], v6 offset:42240
	ds_read_b128 v[104:107], v6 offset:50688
	ds_read_b128 v[108:111], v6 offset:59136
	ds_read_b128 v[112:115], v7
	ds_read_b128 v[116:119], v7 offset:8448
	ds_read_b128 v[120:123], v7 offset:16896
	ds_read_b128 v[124:127], v7 offset:25344
	ds_read_b128 v[136:139], v7 offset:33792
	ds_read_b128 v[140:143], v7 offset:42240
	ds_read_b128 v[144:147], v7 offset:50688
	ds_read_b128 v[148:151], v7 offset:59136
	s_waitcnt vmcnt(15) lgkmcnt(15)
	v_pk_add_f32 v[82:83], v[82:83], v[18:19]
	v_pk_add_f32 v[80:81], v[80:81], v[16:17]
	global_store_dwordx4 v[4:5], v[80:83], off
	s_nop 1
	v_lshl_add_u64 v[4:5], v[4:5], 0, s[100:101]
	s_waitcnt vmcnt(15) lgkmcnt(14)
	v_pk_add_f32 v[86:87], v[86:87], v[22:23]
	v_pk_add_f32 v[84:85], v[84:85], v[20:21]
	global_store_dwordx4 v[4:5], v[84:87], off
	s_nop 1
	v_lshl_add_u64 v[4:5], v[4:5], 0, s[100:101]
	s_waitcnt vmcnt(15) lgkmcnt(13)
	v_pk_add_f32 v[90:91], v[90:91], v[26:27]
	v_pk_add_f32 v[88:89], v[88:89], v[24:25]
	global_store_dwordx4 v[4:5], v[88:91], off
	s_nop 1
	v_lshl_add_u64 v[4:5], v[4:5], 0, s[100:101]
	s_waitcnt vmcnt(15) lgkmcnt(12)
	v_pk_add_f32 v[94:95], v[94:95], v[30:31]
	v_pk_add_f32 v[92:93], v[92:93], v[28:29]
	global_store_dwordx4 v[4:5], v[92:95], off
	s_nop 1
	v_lshl_add_u64 v[4:5], v[4:5], 0, s[100:101]
	s_waitcnt vmcnt(15) lgkmcnt(11)
	v_pk_add_f32 v[98:99], v[98:99], v[34:35]
	v_pk_add_f32 v[96:97], v[96:97], v[32:33]
	global_store_dwordx4 v[4:5], v[96:99], off
	s_nop 1
	v_lshl_add_u64 v[4:5], v[4:5], 0, s[100:101]
	s_waitcnt vmcnt(15) lgkmcnt(10)
	v_pk_add_f32 v[102:103], v[102:103], v[38:39]
	v_pk_add_f32 v[100:101], v[100:101], v[36:37]
	global_store_dwordx4 v[4:5], v[100:103], off
	s_nop 1
	v_lshl_add_u64 v[4:5], v[4:5], 0, s[100:101]
	s_waitcnt vmcnt(15) lgkmcnt(9)
	v_pk_add_f32 v[106:107], v[106:107], v[42:43]
	v_pk_add_f32 v[104:105], v[104:105], v[40:41]
	global_store_dwordx4 v[4:5], v[104:107], off
	s_nop 1
	v_lshl_add_u64 v[4:5], v[4:5], 0, s[100:101]
	s_waitcnt vmcnt(15) lgkmcnt(8)
	v_pk_add_f32 v[110:111], v[110:111], v[46:47]
	v_pk_add_f32 v[108:109], v[108:109], v[44:45]
	global_store_dwordx4 v[4:5], v[108:111], off
	s_nop 1
	v_lshl_add_u64 v[4:5], v[4:5], 0, s[100:101]
	s_waitcnt vmcnt(15) lgkmcnt(7)
	v_pk_add_f32 v[114:115], v[114:115], v[50:51]
	v_pk_add_f32 v[112:113], v[112:113], v[48:49]
	global_store_dwordx4 v[4:5], v[112:115], off
	s_nop 1
	v_lshl_add_u64 v[4:5], v[4:5], 0, s[100:101]
	s_waitcnt vmcnt(15) lgkmcnt(6)
	v_pk_add_f32 v[118:119], v[118:119], v[54:55]
	v_pk_add_f32 v[116:117], v[116:117], v[52:53]
	global_store_dwordx4 v[4:5], v[116:119], off
	s_nop 1
	v_lshl_add_u64 v[4:5], v[4:5], 0, s[100:101]
	s_waitcnt vmcnt(15) lgkmcnt(5)
	v_pk_add_f32 v[122:123], v[122:123], v[58:59]
	v_pk_add_f32 v[120:121], v[120:121], v[56:57]
	global_store_dwordx4 v[4:5], v[120:123], off
	s_nop 1
	v_lshl_add_u64 v[4:5], v[4:5], 0, s[100:101]
	s_waitcnt vmcnt(15) lgkmcnt(4)
	v_pk_add_f32 v[126:127], v[126:127], v[62:63]
	v_pk_add_f32 v[124:125], v[124:125], v[60:61]
	global_store_dwordx4 v[4:5], v[124:127], off
	s_nop 1
	v_lshl_add_u64 v[4:5], v[4:5], 0, s[100:101]
	s_waitcnt vmcnt(15) lgkmcnt(3)
	v_pk_add_f32 v[138:139], v[138:139], v[66:67]
	v_pk_add_f32 v[136:137], v[136:137], v[64:65]
	global_store_dwordx4 v[4:5], v[136:139], off
	s_nop 1
	v_lshl_add_u64 v[4:5], v[4:5], 0, s[100:101]
	s_waitcnt vmcnt(15) lgkmcnt(2)
	v_pk_add_f32 v[142:143], v[142:143], v[70:71]
	v_pk_add_f32 v[140:141], v[140:141], v[68:69]
	global_store_dwordx4 v[4:5], v[140:143], off
	s_nop 1
	v_lshl_add_u64 v[4:5], v[4:5], 0, s[100:101]
	s_waitcnt vmcnt(15) lgkmcnt(1)
	v_pk_add_f32 v[146:147], v[146:147], v[74:75]
	v_pk_add_f32 v[144:145], v[144:145], v[72:73]
	global_store_dwordx4 v[4:5], v[144:147], off
	s_nop 1
	v_lshl_add_u64 v[4:5], v[4:5], 0, s[100:101]
	s_waitcnt vmcnt(15) lgkmcnt(0)
	v_pk_add_f32 v[150:151], v[150:151], v[78:79]
	v_pk_add_f32 v[148:149], v[148:149], v[76:77]
	global_store_dwordx4 v[4:5], v[148:151], off
	s_add_i32 s24, s24, s72
	s_cmpk_gt_i32 s24, 0x3ff
	s_waitcnt lgkmcnt(0)
	s_barrier
	s_cbranch_scc0 .LBB0_918
